# attention: K/V LDS-DMA for tile t+2 issued between the PV MFMAs instead of at the head of each KV iteration
# speedup vs baseline: 1.0268x; 1.0268x over previous
; #define SBAR() __builtin_amdgcn_sched_barrier(0)
; __device__ __forceinline__ s16x4 vtr(lds_cptr p){ return __builtin_bit_cast(s16x4,__builtin_amdgcn_ds_read_tr16_b64_v4i16((__attribute__((address_space(3))) v4i16_t*)p)); }
;   #define DMA_K(t,s3) glds16(ksrc+(long)(t)*KVBLK*DM,(unsigned)__builtin_amdgcn_readfirstlane(kdst+(s3)*SLOTB))
;   #define DMA_V(t,s3) do{ const unsigned vd_=(unsigned)__builtin_amdgcn_readfirstlane(vdst+(s3)*VSLOTB); glds16(vsrc+(long)(t)*KVBLK*DM,vd_); glds16(vsrc+(long)(t)*KVBLK*DM+64,(unsigned)__builtin_amdgcn_readfirstlane(vd_+8192)); }while(0)
; template<int THRL> __device__ __forceinline__ void attn_unit(int qb,const bf16*Q,const bf16*__restrict__ K,const bf16*__restrict__ V,bf16*O,char*shm){
;     ...
;     if(t+2<NT){DMA_K(t+2,c2);DMA_V(t+2,c2);}
;     bf16x8 kf[8]; kload8(kf,kp0+c0*SLOTB);
;     SBAR();
;     f32x16 C0,C1;
;     {
;       C0=__builtin_amdgcn_mfma_f32_32x32x16_bf16(kf[0],qr[0],negm,0,0,0); C1=__builtin_amdgcn_mfma_f32_32x32x16_bf16(kf[1],qr[0],negm,0,0,0);
;       C0=__builtin_amdgcn_mfma_f32_32x32x16_bf16(kf[2],qr[1],C0,0,0,0);   C1=__builtin_amdgcn_mfma_f32_32x32x16_bf16(kf[3],qr[1],C1,0,0,0);
;       C0=__builtin_amdgcn_mfma_f32_32x32x16_bf16(kf[4],qr[2],C0,0,0,0);   C1=__builtin_amdgcn_mfma_f32_32x32x16_bf16(kf[5],qr[2],C1,0,0,0);
;       C0=__builtin_amdgcn_mfma_f32_32x32x16_bf16(kf[6],qr[3],C0,0,0,0);   C1=__builtin_amdgcn_mfma_f32_32x32x16_bf16(kf[7],qr[3],C1,0,0,0); }
;     SBAR();
;     const lds_cptr vp_=vp0+c0*VSLOTB; s16x4 vl_[8],vh_[8];
;     #pragma unroll
;     for(int k2=0;k2<2;++k2)
;       #pragma unroll
;       for(int d_=0;d_<4;++d_){ vl_[d_*2+k2]=vtr(vp_+(d_*4096+k2*1024)); vh_[d_*2+k2]=vtr(vp_+(d_*4096+k2*1024+512)); }
;     SBAR();
;     { const int jb_=t-(NT-4); if(jb_>=0)cmask(C0,C1,jb_,qrel,hi); }
.LBB0_364:
	s_add_i32 s12, s31, 2
	s_cmp_ge_i32 s12, s26
	s_cselect_b64 s[12:13], -1, 0
	s_mov_b32 s34, s35
	s_and_b64 vcc, exec, s[12:13]
.LBB0_366:
	v_lshl_add_u32 v80, s34, 13, v189
	ds_read_b128 v[96:99], v80
	ds_read_b128 v[128:131], v80 offset:512
	ds_read_b128 v[100:103], v80 offset:2048
	ds_read_b128 v[132:135], v80 offset:2560
	ds_read_b128 v[104:107], v80 offset:4096
	ds_read_b128 v[144:147], v80 offset:4608
	ds_read_b128 v[108:111], v80 offset:6144
	ds_read_b128 v[194:197], v80 offset:6656
	s_waitcnt lgkmcnt(7)
	v_mfma_f32_32x32x16_bf16 v[80:95], v[96:99], v[112:115], v[64:79]
	s_waitcnt lgkmcnt(5)
	v_mfma_f32_32x32x16_bf16 v[80:95], v[100:103], v[116:119], v[80:95]
	s_waitcnt lgkmcnt(3)
	v_mfma_f32_32x32x16_bf16 v[80:95], v[104:107], v[120:123], v[80:95]
	s_waitcnt lgkmcnt(1)
	v_mfma_f32_32x32x16_bf16 v[80:95], v[108:111], v[124:127], v[80:95]
	v_mov_b64_e32 v[110:111], v[78:79]
	v_mov_b64_e32 v[108:109], v[76:77]
	v_mov_b64_e32 v[106:107], v[74:75]
	v_mov_b64_e32 v[104:105], v[72:73]
	v_mov_b64_e32 v[102:103], v[70:71]
	v_mov_b64_e32 v[100:101], v[68:69]
	v_mov_b64_e32 v[98:99], v[66:67]
	v_mov_b64_e32 v[96:97], v[64:65]
	s_lshl_b32 s14, s34, 14
	v_add_u32_e32 v193, s14, v190
	v_mfma_f32_32x32x16_bf16 v[96:111], v[128:131], v[112:115], v[96:111]
	ds_read_b64_tr_b16 v[156:157], v193 offset:24576
	ds_read_b64_tr_b16 v[158:159], v193 offset:25088
	ds_read_b64_tr_b16 v[140:141], v193 offset:25600
	ds_read_b64_tr_b16 v[142:143], v193 offset:26112
	ds_read_b64_tr_b16 v[152:153], v193 offset:28672
	ds_read_b64_tr_b16 v[154:155], v193 offset:29184
	ds_read_b64_tr_b16 v[136:137], v193 offset:29696
	ds_read_b64_tr_b16 v[138:139], v193 offset:30208
	v_mfma_f32_32x32x16_bf16 v[96:111], v[132:135], v[116:119], v[96:111]
	v_mfma_f32_32x32x16_bf16 v[96:111], v[144:147], v[120:123], v[96:111]
	ds_read_b64_tr_b16 v[148:149], v193 offset:32768
	ds_read_b64_tr_b16 v[150:151], v193 offset:33280
	ds_read_b64_tr_b16 v[132:133], v193 offset:33792
	ds_read_b64_tr_b16 v[134:135], v193 offset:34304
	ds_read_b64_tr_b16 v[144:145], v193 offset:36864
	ds_read_b64_tr_b16 v[146:147], v193 offset:37376
	ds_read_b64_tr_b16 v[128:129], v193 offset:37888
	ds_read_b64_tr_b16 v[130:131], v193 offset:38400
	s_waitcnt lgkmcnt(14)
	v_mfma_f32_32x32x16_bf16 v[96:111], v[194:197], v[124:127], v[96:111]
	s_add_i32 s14, s28, s31
	s_cmp_lt_i32 s14, -4
	s_cbranch_scc1 .LBB0_368
	v_subrev_u32_e32 v163, 27, v192
	v_subrev_u32_e32 v162, 59, v192
	v_cmp_le_i32_e32 vcc, v163, v188
	s_nop 5
	v_cndmask_b32_e32 v96, v229, v96, vcc
	v_cmp_lt_i32_e32 vcc, v162, v188
	s_nop 1
	v_cndmask_b32_e32 v81, v229, v81, vcc
	v_cmp_le_i32_e32 vcc, v162, v188
	v_subrev_u32_e32 v162, 26, v192
	s_nop 0
	v_cndmask_b32_e32 v80, v229, v80, vcc
	v_cmp_le_i32_e32 vcc, v162, v188
	v_subrev_u32_e32 v162, 57, v192
	s_nop 0
	v_cndmask_b32_e32 v97, v229, v97, vcc
	v_cmp_le_i32_e32 vcc, v162, v188
	v_subrev_u32_e32 v162, 25, v192
	s_nop 0
	v_cndmask_b32_e32 v82, v229, v82, vcc
	v_cmp_le_i32_e32 vcc, v162, v188
	v_subrev_u32_e32 v162, 56, v192
	s_nop 0
	v_cndmask_b32_e32 v98, v229, v98, vcc
	v_cmp_le_i32_e32 vcc, v162, v188
	v_subrev_u32_e32 v162, 24, v192
	s_nop 0
	v_cndmask_b32_e32 v83, v229, v83, vcc
	v_cmp_le_i32_e32 vcc, v162, v188
	v_subrev_u32_e32 v162, 51, v192
	s_nop 0
	v_cndmask_b32_e32 v99, v229, v99, vcc
	v_cmp_le_i32_e32 vcc, v162, v188
	v_subrev_u32_e32 v162, 19, v192
	s_nop 0
	v_cndmask_b32_e32 v84, v229, v84, vcc
	v_cmp_le_i32_e32 vcc, v162, v188
	v_subrev_u32_e32 v162, 50, v192
	s_nop 0
	v_cndmask_b32_e32 v100, v229, v100, vcc
	v_cmp_le_i32_e32 vcc, v162, v188
	v_subrev_u32_e32 v162, 18, v192
	s_nop 0
	v_cndmask_b32_e32 v85, v229, v85, vcc
	v_cmp_le_i32_e32 vcc, v162, v188
	v_subrev_u32_e32 v162, 49, v192
	s_nop 0
	v_cndmask_b32_e32 v101, v229, v101, vcc
	v_cmp_le_i32_e32 vcc, v162, v188
	v_subrev_u32_e32 v162, 17, v192
	s_nop 0
	v_cndmask_b32_e32 v86, v229, v86, vcc
	v_cmp_le_i32_e32 vcc, v162, v188
	v_subrev_u32_e32 v162, 48, v192
	s_nop 0
	v_cndmask_b32_e32 v102, v229, v102, vcc
	v_cmp_le_i32_e32 vcc, v162, v188
	v_add_u32_e32 v162, -16, v192
	s_nop 0
	v_cndmask_b32_e32 v87, v229, v87, vcc
	v_cmp_le_i32_e32 vcc, v162, v188
	v_subrev_u32_e32 v162, 43, v192
	s_nop 0
	v_cndmask_b32_e32 v103, v229, v103, vcc
	v_cmp_le_i32_e32 vcc, v162, v188
	v_add_u32_e32 v162, -11, v192
	s_nop 0
	v_cndmask_b32_e32 v88, v229, v88, vcc
	v_cmp_le_i32_e32 vcc, v162, v188
	v_subrev_u32_e32 v162, 42, v192
	s_nop 0
	v_cndmask_b32_e32 v104, v229, v104, vcc
	v_cmp_le_i32_e32 vcc, v162, v188
	v_add_u32_e32 v162, -10, v192
	s_nop 0
	v_cndmask_b32_e32 v89, v229, v89, vcc
	v_cmp_le_i32_e32 vcc, v162, v188
	v_subrev_u32_e32 v162, 41, v192
	s_nop 0
	v_cndmask_b32_e32 v105, v229, v105, vcc
	v_cmp_le_i32_e32 vcc, v162, v188
	v_add_u32_e32 v162, -9, v192
	s_nop 0
	v_cndmask_b32_e32 v90, v229, v90, vcc
	v_cmp_le_i32_e32 vcc, v162, v188
	v_subrev_u32_e32 v162, 40, v192
	s_nop 0
	v_cndmask_b32_e32 v106, v229, v106, vcc
	v_cmp_le_i32_e32 vcc, v162, v188
	v_add_u32_e32 v162, -8, v192
	s_nop 0
	v_cndmask_b32_e32 v91, v229, v91, vcc
	v_cmp_le_i32_e32 vcc, v162, v188
	v_subrev_u32_e32 v162, 35, v192
	s_nop 0
	v_cndmask_b32_e32 v107, v229, v107, vcc
	v_cmp_le_i32_e32 vcc, v162, v188
	v_add_u32_e32 v162, -3, v192
	s_nop 0
	v_cndmask_b32_e32 v92, v229, v92, vcc
	v_cmp_le_i32_e32 vcc, v162, v188
	v_subrev_u32_e32 v162, 34, v192
	s_nop 0
	v_cndmask_b32_e32 v108, v229, v108, vcc
	v_cmp_le_i32_e32 vcc, v162, v188
	v_add_u32_e32 v162, -2, v192
	s_nop 0
	v_cndmask_b32_e32 v93, v229, v93, vcc
	v_cmp_le_i32_e32 vcc, v162, v188
	v_subrev_u32_e32 v162, 33, v192
	s_nop 0
	v_cndmask_b32_e32 v109, v229, v109, vcc
	v_cmp_le_i32_e32 vcc, v162, v188
	v_add_u32_e32 v162, -1, v192
	s_nop 0
	v_cndmask_b32_e32 v94, v229, v94, vcc
	v_cmp_le_i32_e32 vcc, v162, v188
	v_subrev_u32_e32 v162, 32, v192
	s_nop 0
	v_cndmask_b32_e32 v110, v229, v110, vcc
	v_cmp_le_i32_e32 vcc, v162, v188
	s_nop 1
	v_cndmask_b32_e32 v95, v229, v95, vcc
	v_cmp_le_i32_e32 vcc, v192, v188
	s_nop 1
	v_cndmask_b32_e32 v111, v229, v111, vcc

; #define SBAR() __builtin_amdgcn_sched_barrier(0)
; #define WAIT_BAR(N) asm volatile("s_waitcnt vmcnt(" #N ") lgkmcnt(0)\n\ts_barrier":::"memory")
; __device__ __forceinline__ s16x4 vtr(lds_cptr p){ return __builtin_bit_cast(s16x4,__builtin_amdgcn_ds_read_tr16_b64_v4i16((__attribute__((address_space(3))) v4i16_t*)p)); }
;   #define DMA_K(t,s3) glds16(ksrc+(long)(t)*KVBLK*DM,(unsigned)__builtin_amdgcn_readfirstlane(kdst+(s3)*SLOTB))
;   #define PKW(P,B) cvtpk_s(P[B],P[B+1])
; template<int THRL> __device__ __forceinline__ void attn_unit(int qb,const bf16*Q,const bf16*__restrict__ K,const bf16*__restrict__ V,bf16*O,char*shm){
;     ...
;     if(t+2<NT){DMA_K(t+2,c2);DMA_V(t+2,c2);}
;     ...
;     for(int r=0;r<16;++r){C0[r]=__builtin_amdgcn_exp2f(C0[r]);C1[r]=__builtin_amdgcn_exp2f(C1[r]);}
;     { float s0=C0[0]+C0[1],s1=C1[0]+C1[1];
;       #pragma unroll
;       for(int r=2;r<16;++r){s0+=C0[r];s1+=C1[r];}
;       l_reg+=s0+s1; }
;     const u32x4 pw0=(u32x4){PKW(C0,0),PKW(C0,2),PKW(C0,4),PKW(C0,6)},pw1=(u32x4){PKW(C0,8),PKW(C0,10),PKW(C0,12),PKW(C0,14)},pw2=(u32x4){PKW(C1,0),PKW(C1,2),PKW(C1,4),PKW(C1,6)},pw3=(u32x4){PKW(C1,8),PKW(C1,10),PKW(C1,12),PKW(C1,14)};
;     SBAR();
;     ...
;     s16x4 w2l_[4],w2h_[4],w3l_[4],w3h_[4];
;     #pragma unroll
;     for(int d_=0;d_<4;++d_){ w2l_[d_]=vtr(vp_+(d_*4096+2*1024)); w2h_[d_]=vtr(vp_+(d_*4096+2*1024+512)); }
;     SBAR();
;     #pragma unroll
;     for(int d_=0;d_<4;++d_){ o[d_]=__builtin_amdgcn_mfma_f32_32x32x16_bf16(__builtin_bit_cast(bf16x8,pw0),VFRAG(vl_,vh_,d_*2),o[d_],0,0,0); }
;     SBAR();
;     #pragma unroll
;     for(int d_=0;d_<4;++d_){ w3l_[d_]=vtr(vp_+(d_*4096+3*1024)); w3h_[d_]=vtr(vp_+(d_*4096+3*1024+512)); }
;     SBAR();
;     #pragma unroll
;     for(int d_=0;d_<4;++d_){ o[d_]=__builtin_amdgcn_mfma_f32_32x32x16_bf16(__builtin_bit_cast(bf16x8,pw1),VFRAG(vl_,vh_,d_*2+1),o[d_],0,0,0); }
;     #pragma unroll
;     for(int d_=0;d_<4;++d_){ o[d_]=__builtin_amdgcn_mfma_f32_32x32x16_bf16(__builtin_bit_cast(bf16x8,pw2),VFRAG(w2l_,w2h_,d_),o[d_],0,0,0); }
;     #pragma unroll
;     for(int d_=0;d_<4;++d_){ o[d_]=__builtin_amdgcn_mfma_f32_32x32x16_bf16(__builtin_bit_cast(bf16x8,pw3),VFRAG(w3l_,w3h_,d_),o[d_],0,0,0); }
;     SBAR();
;     ...
;     if(t+2<NT){WAIT_BAR(3);}else{WAIT_BAR(0);}
.LBB0_372:
	v_exp_f32_e32 v80, v80
	v_exp_f32_e32 v96, v96
	v_exp_f32_e32 v81, v81
	v_exp_f32_e32 v97, v97
	v_exp_f32_e32 v82, v82
	v_exp_f32_e32 v98, v98
	v_exp_f32_e32 v83, v83
	v_exp_f32_e32 v99, v99
	v_exp_f32_e32 v84, v84
	v_exp_f32_e32 v100, v100
	v_exp_f32_e32 v85, v85
	v_exp_f32_e32 v101, v101
	v_exp_f32_e32 v86, v86
	v_exp_f32_e32 v102, v102
	v_exp_f32_e32 v87, v87
	v_exp_f32_e32 v103, v103
	v_exp_f32_e32 v88, v88
	v_exp_f32_e32 v104, v104
	v_exp_f32_e32 v89, v89
	v_exp_f32_e32 v105, v105
	v_exp_f32_e32 v90, v90
	v_exp_f32_e32 v106, v106
	v_exp_f32_e32 v91, v91
	v_exp_f32_e32 v107, v107
	v_exp_f32_e32 v92, v92
	v_exp_f32_e32 v108, v108
	v_exp_f32_e32 v93, v93
	v_exp_f32_e32 v109, v109
	v_exp_f32_e32 v94, v94
	v_exp_f32_e32 v110, v110
	v_exp_f32_e32 v95, v95
	v_exp_f32_e32 v111, v111
	v_cvt_pk_bf16_f32 v194, v80, v81
	v_cvt_pk_bf16_f32 v195, v82, v83
	v_cvt_pk_bf16_f32 v196, v84, v85
	v_cvt_pk_bf16_f32 v197, v86, v87
	v_cvt_pk_bf16_f32 v198, v88, v89
	v_cvt_pk_bf16_f32 v199, v90, v91
	v_cvt_pk_bf16_f32 v200, v92, v93
	v_cvt_pk_bf16_f32 v201, v94, v95
	v_cvt_pk_bf16_f32 v202, v96, v97
	v_cvt_pk_bf16_f32 v203, v98, v99
	v_cvt_pk_bf16_f32 v204, v100, v101
	v_cvt_pk_bf16_f32 v205, v102, v103
	v_cvt_pk_bf16_f32 v206, v104, v105
	v_cvt_pk_bf16_f32 v207, v106, v107
	v_cvt_pk_bf16_f32 v208, v108, v109
	v_cvt_pk_bf16_f32 v209, v110, v111
	s_and_b64 vcc, exec, s[12:13]
	ds_read_b64_tr_b16 v[210:211], v193 offset:26624
	ds_read_b64_tr_b16 v[212:213], v193 offset:27136
	ds_read_b64_tr_b16 v[214:215], v193 offset:30720
	ds_read_b64_tr_b16 v[216:217], v193 offset:31232
	ds_read_b64_tr_b16 v[218:219], v193 offset:34816
	ds_read_b64_tr_b16 v[220:221], v193 offset:35328
	ds_read_b64_tr_b16 v[232:233], v193 offset:38912
	ds_read_b64_tr_b16 v[234:235], v193 offset:39424
	v_mfma_f32_32x32x16_bf16 v[48:63], v[194:197], v[156:159], v[48:63]
	s_waitcnt lgkmcnt(14)
	v_mfma_f32_32x32x16_bf16 v[32:47], v[194:197], v[152:155], v[32:47]
	s_cbranch_vccnz .Lattn_nodma0
	s_lshl_b32 s14, s29, 13
	s_add_i32 s14, s14, s9
	s_mov_b32 m0, s14
	s_nop 0
	global_load_lds_dwordx4 v[182:183], off
.Lattn_nodma0:
	v_mfma_f32_32x32x16_bf16 v[16:31], v[194:197], v[148:151], v[16:31]
	s_waitcnt lgkmcnt(10)
	v_mfma_f32_32x32x16_bf16 v[0:15], v[194:197], v[144:147], v[0:15]
	ds_read_b64_tr_b16 v[144:145], v193 offset:27648
	ds_read_b64_tr_b16 v[146:147], v193 offset:28160
	ds_read_b64_tr_b16 v[148:149], v193 offset:31744
	ds_read_b64_tr_b16 v[150:151], v193 offset:32256
	ds_read_b64_tr_b16 v[152:153], v193 offset:35840
	ds_read_b64_tr_b16 v[154:155], v193 offset:36352
	ds_read_b64_tr_b16 v[156:157], v193 offset:39936
	ds_read_b64_tr_b16 v[158:159], v193 offset:40448
	v_mfma_f32_32x32x16_bf16 v[48:63], v[198:201], v[140:143], v[48:63]
	v_mfma_f32_32x32x16_bf16 v[32:47], v[198:201], v[136:139], v[32:47]
	s_cbranch_vccnz .Lattn_nodma1
	s_lshl_b32 s14, s29, 14
	s_add_i32 s14, s14, s11
	s_mov_b32 m0, s14
	v_lshl_add_u64 v[162:163], v[180:181], 0, s[50:51]
	global_load_lds_dwordx4 v[180:181], off
.Lattn_nodma1:
	v_mfma_f32_32x32x16_bf16 v[16:31], v[198:201], v[132:135], v[16:31]
	s_waitcnt lgkmcnt(14)
	v_mfma_f32_32x32x16_bf16 v[0:15], v[198:201], v[128:131], v[0:15]
	v_mfma_f32_32x32x16_bf16 v[48:63], v[202:205], v[210:213], v[48:63]
	s_waitcnt lgkmcnt(12)
	v_mfma_f32_32x32x16_bf16 v[32:47], v[202:205], v[214:217], v[32:47]
	s_cbranch_vccnz .Lattn_nodma2
	s_addk_i32 s14, 0x2000
	s_mov_b32 m0, s14
	s_nop 0
	global_load_lds_dwordx4 v[162:163], off
.Lattn_nodma2:
	s_waitcnt lgkmcnt(10)
	v_mfma_f32_32x32x16_bf16 v[16:31], v[202:205], v[218:221], v[16:31]
	s_waitcnt lgkmcnt(8)
	v_mfma_f32_32x32x16_bf16 v[0:15], v[202:205], v[232:235], v[0:15]
	s_waitcnt lgkmcnt(6)
	v_mfma_f32_32x32x16_bf16 v[48:63], v[206:209], v[144:147], v[48:63]
	s_waitcnt lgkmcnt(4)
	v_mfma_f32_32x32x16_bf16 v[32:47], v[206:209], v[148:151], v[32:47]
	s_waitcnt lgkmcnt(2)
	v_mfma_f32_32x32x16_bf16 v[16:31], v[206:209], v[152:155], v[16:31]
	s_waitcnt lgkmcnt(0)
	v_mfma_f32_32x32x16_bf16 v[0:15], v[206:209], v[156:159], v[0:15]
	s_mov_b64 s[14:15], -1
	s_and_b64 vcc, exec, s[12:13]
	s_cbranch_vccz .LBB0_374
	s_waitcnt vmcnt(0) lgkmcnt(0)
	s_barrier
	s_mov_b64 s[14:15], 0
